# out-proj GEMM: first K-iteration of non-first units peeled with vmcnt(24) in its first two phases (overlaps the epilogue store tail)
# speedup vs baseline: 1.0028x; 1.0007x over previous
; #define PG8_STAGE(bufoff, gbase, voff) do { _Pragma("unroll") for (int _i = 0; _i < 2; ++_i) \
;         __builtin_amdgcn_global_load_lds((const unsigned*)((const char*)(gbase) + (voff)[_i]), (LAS unsigned*)(lds + (bufoff) + ldsw + _i * 8192), 16, 0, 0); } while (0)
; #define PG8_LDA(dst, b, h) do { _Pragma("unroll") for (int m = 0; m < 4; ++m) _Pragma("unroll") for (int k = 0; k < 2; ++k) dst[m][k] = *(const LAS bf16x8*)(lds + PG8_SA(b, h) + aoff + m * 2048 + k * 1024); } while (0)
; #define PG8_LDB(dst, b, h) do { _Pragma("unroll") for (int n = 0; n < 2; ++n) _Pragma("unroll") for (int k = 0; k < 2; ++k) dst[n][k] = *(const LAS bf16x8*)(lds + PG8_SB(b, h) + boff + n * 2048 + k * 1024); } while (0)
; #define PG8_WAIT_V(n) asm volatile("s_waitcnt vmcnt(" #n ")" ::: "memory")
; #define PG8_WAIT_L(n) asm volatile("s_waitcnt lgkmcnt(" #n ")" ::: "memory")
; #define PG8_BAR __builtin_amdgcn_s_barrier()
; #define PG8_SCHED __builtin_amdgcn_sched_barrier(0)
; template <class Epi, class Sched>
; __device__ __forceinline__ void gemm_phase(LAS unsigned char* lds, const Gemm g, const Sched& S, const Epi& E, const int wid) {
;     ...
;     for (;;) {
;         const bool has_next = S.next(ui + 1, nxt);
;         const char* nA = has_next ? (const char*)g.A + (size_t)nxt.pm * tstep : cA; const char* nB = has_next ? (const char*)g.Bt + (size_t)nxt.pn * tstep : cB;
;         for (int t = 0; t < nt; t += 2) {
;             const bool last = (t == nt - 2);
;             const char* a1 = cA + (size_t)(t + 1) * kstep;
;             const char* a2 = last ? nA : cA + (size_t)(t + 2) * kstep; const char* b2 = last ? nB : cB + (size_t)(t + 2) * kstep;
;             const char* a3 = a2 + kstep; const char* b3 = b2 + kstep;
;             if constexpr (Epi::MID) { if (t == nt / 2) E.mid(acc, cur, ui, wr, wc, fr, fq); }
;             PG8_LDB(B0, 0, 0); PG8_LDB(B1, 0, 1); PG8_SCHED; PG8_LDA(At, 0, 0); PG8_STAGE(PG8_SA(1, 1), a1 + hstep, voffA);
;             PG8_WAIT_V(8); PG8_WAIT_L(0); PG8_BAR; PG8_MMA(0, 0, At, B0); PG8_MMA(0, 1, At, B1); PG8_BAR; PG8_SCHED;
;             PG8_LDA(At, 0, 1); PG8_STAGE(PG8_SB(0, 0), b2, voffB); PG8_STAGE(PG8_SB(0, 1), b2 + bstep, voffB); PG8_STAGE(PG8_SA(0, 0), a2, voffA);
;             PG8_WAIT_V(8); PG8_WAIT_L(0); PG8_BAR; PG8_MMA(1, 0, At, B0); PG8_MMA(1, 1, At, B1); PG8_BAR; PG8_SCHED;
.LBB0_641:
	s_ashr_i32 s9, s8, 31
	s_lshl_b64 s[10:11], s[8:9], 20
	s_add_u32 s10, s36, s10
	s_addc_u32 s11, s37, s11
	s_and_b64 s[12:13], s[42:43], exec
	s_cselect_b32 s9, s11, s15
	s_cselect_b32 s39, s10, s14
	s_ashr_i32 s1, s0, 31
	s_lshl_b64 s[12:13], s[0:1], 20
	s_add_u32 s12, s7, s12
	s_addc_u32 s13, s22, s13
	s_and_b64 s[20:21], s[42:43], exec
	s_mul_i32 s1, s18, 0xc00
	s_cselect_b32 s44, s13, s17
	s_cselect_b32 s46, s12, s16
	s_add_i32 s1, s1, 0
	s_add_i32 s1, s1, 0x20000
	s_add_u32 s18, s14, 0x80080
	s_addc_u32 s19, s15, 0
	s_add_u32 s47, s16, 0x100
	v_lshl_add_u64 v[140:141], s[18:19], 0, v[136:137]
	v_lshl_add_u64 v[142:143], s[18:19], 0, v[138:139]
	s_addc_u32 s49, s17, 0
	s_mov_b32 s51, -2
	s_mov_b64 s[16:17], 0
	s_cmp_eq_u32 s34, 1
	s_cbranch_scc1 .LBB0_643
	s_add_u32 s18, s14, s16
	s_addc_u32 s19, s15, s17
	s_add_u32 s18, s18, 0x100
	s_addc_u32 s19, s19, 0
	s_add_u32 s78, s47, s16
	s_addc_u32 s79, s49, s17
	s_cmpk_eq_i32 s16, 0xf00
	s_cselect_b32 s21, s9, s19
	s_cselect_b32 s20, s39, s18
	s_cselect_b32 s19, s44, s79
	s_cselect_b32 s18, s46, s78
	s_add_i32 s78, 0, 0x10000
	v_add_u32_e32 v148, s78, v155
	s_add_i32 s80, 0, 0x14000
	ds_read_b128 v[144:147], v148
	ds_read_b128 v[158:161], v148 offset:1024
	ds_read_b128 v[162:165], v148 offset:2048
	ds_read_b128 v[166:169], v148 offset:3072
	v_add_u32_e32 v148, s80, v155
	ds_read_b128 v[170:173], v148
	ds_read_b128 v[174:177], v148 offset:1024
	ds_read_b128 v[178:181], v148 offset:2048
	ds_read_b128 v[194:197], v148 offset:3072
	v_lshl_add_u64 v[148:149], v[140:141], 0, s[16:17]
	s_add_i32 m0, s23, 0xc000
	ds_read_b128 v[198:201], v156
	ds_read_b128 v[202:205], v156 offset:1024
	ds_read_b128 v[206:209], v156 offset:2048
	ds_read_b128 v[210:213], v156 offset:3072
	ds_read_b128 v[214:217], v156 offset:4096
	ds_read_b128 v[218:221], v156 offset:5120
	ds_read_b128 v[222:225], v156 offset:6144
	ds_read_b128 v[226:229], v156 offset:7168
	global_load_lds_dwordx4 v[148:149], off
	v_lshl_add_u64 v[148:149], v[142:143], 0, s[16:17]
	s_add_i32 m0, s23, 0xe000
	s_nop 0
	global_load_lds_dwordx4 v[148:149], off
	s_waitcnt vmcnt(24)
	s_waitcnt lgkmcnt(0)
	s_barrier
	s_setprio 1
	s_waitcnt lgkmcnt(0)
	v_mfma_f32_16x16x32_bf16 v[18:21], v[144:147], v[198:201], v[18:21]
	v_mfma_f32_16x16x32_bf16 v[38:41], v[162:165], v[198:201], v[38:41]
	v_mfma_f32_16x16x32_bf16 v[6:9], v[144:147], v[206:209], v[6:9]
	v_mfma_f32_16x16x32_bf16 v[26:29], v[162:165], v[206:209], v[26:29]
	v_mfma_f32_16x16x32_bf16 v[2:5], v[144:147], v[214:217], v[2:5]
	v_mfma_f32_16x16x32_bf16 v[14:17], v[162:165], v[214:217], v[14:17]
	v_mfma_f32_16x16x32_bf16 v[118:121], v[144:147], v[222:225], v[118:121]
	v_mfma_f32_16x16x32_bf16 v[126:129], v[162:165], v[222:225], v[126:129]
	v_mfma_f32_16x16x32_bf16 v[18:21], v[158:161], v[202:205], v[18:21]
	v_mfma_f32_16x16x32_bf16 v[38:41], v[166:169], v[202:205], v[38:41]
	v_mfma_f32_16x16x32_bf16 v[6:9], v[158:161], v[210:213], v[6:9]
	v_mfma_f32_16x16x32_bf16 v[26:29], v[166:169], v[210:213], v[26:29]
	v_mfma_f32_16x16x32_bf16 v[2:5], v[158:161], v[218:221], v[2:5]
	v_mfma_f32_16x16x32_bf16 v[14:17], v[166:169], v[218:221], v[14:17]
	v_mfma_f32_16x16x32_bf16 v[118:121], v[158:161], v[226:229], v[118:121]
	v_mfma_f32_16x16x32_bf16 v[126:129], v[166:169], v[226:229], v[126:129]
	s_setprio 0
	s_setprio 1
	v_mfma_f32_16x16x32_bf16 v[34:37], v[170:173], v[198:201], v[34:37]
	v_mfma_f32_16x16x32_bf16 v[54:57], v[178:181], v[198:201], v[54:57]
	v_mfma_f32_16x16x32_bf16 v[22:25], v[170:173], v[206:209], v[22:25]
	v_mfma_f32_16x16x32_bf16 v[42:45], v[178:181], v[206:209], v[42:45]
	v_mfma_f32_16x16x32_bf16 v[10:13], v[170:173], v[214:217], v[10:13]
	v_mfma_f32_16x16x32_bf16 v[30:33], v[178:181], v[214:217], v[30:33]
	v_mfma_f32_16x16x32_bf16 v[114:117], v[170:173], v[222:225], v[114:117]
	v_mfma_f32_16x16x32_bf16 v[122:125], v[178:181], v[222:225], v[122:125]
	v_mfma_f32_16x16x32_bf16 v[34:37], v[174:177], v[202:205], v[34:37]
	v_mfma_f32_16x16x32_bf16 v[54:57], v[194:197], v[202:205], v[54:57]
	v_mfma_f32_16x16x32_bf16 v[22:25], v[174:177], v[210:213], v[22:25]
	v_mfma_f32_16x16x32_bf16 v[42:45], v[194:197], v[210:213], v[42:45]
	v_mfma_f32_16x16x32_bf16 v[10:13], v[174:177], v[218:221], v[10:13]
	v_mfma_f32_16x16x32_bf16 v[30:33], v[194:197], v[218:221], v[30:33]
	v_mfma_f32_16x16x32_bf16 v[114:117], v[174:177], v[226:229], v[114:117]
	v_mfma_f32_16x16x32_bf16 v[122:125], v[194:197], v[226:229], v[122:125]
	s_setprio 0
	s_barrier
	s_add_i32 s78, s78, s97
	v_lshl_add_u64 v[148:149], s[18:19], 0, v[0:1]
	s_mov_b32 m0, s78
	ds_read_b128 v[198:201], v156 offset:16384
	ds_read_b128 v[202:205], v156 offset:17408
	ds_read_b128 v[206:209], v156 offset:18432
	ds_read_b128 v[210:213], v156 offset:19456
	ds_read_b128 v[214:217], v156 offset:20480
	ds_read_b128 v[218:221], v156 offset:21504
	ds_read_b128 v[222:225], v156 offset:22528
	ds_read_b128 v[226:229], v156 offset:23552
	global_load_lds_dwordx4 v[148:149], off
	s_add_i32 m0, s78, 0x2000
	s_add_u32 s78, s18, 0x20000
	v_lshl_add_u64 v[152:153], s[18:19], 0, v[130:131]
	s_addc_u32 s79, s19, 0
	s_add_i32 s80, s80, s97
	global_load_lds_dwordx4 v[152:153], off
	v_lshl_add_u64 v[182:183], s[78:79], 0, v[0:1]
	s_mov_b32 m0, s80
	v_lshl_add_u64 v[188:189], s[20:21], 0, v[132:133]
	global_load_lds_dwordx4 v[182:183], off
	v_lshl_add_u64 v[182:183], s[78:79], 0, v[130:131]
	s_add_i32 m0, s80, 0x2000
	s_nop 0
	global_load_lds_dwordx4 v[182:183], off
	v_lshl_add_u64 v[182:183], s[20:21], 0, v[134:135]
	s_mov_b32 m0, s23
	s_nop 0
	global_load_lds_dwordx4 v[182:183], off
	s_mov_b32 m0, s24
	s_nop 0
	global_load_lds_dwordx4 v[188:189], off
	s_waitcnt vmcnt(24)
	s_waitcnt lgkmcnt(0)
	s_barrier
; #define PG8_STAGE(bufoff, gbase, voff) do { _Pragma("unroll") for (int _i = 0; _i < 2; ++_i) \
;         __builtin_amdgcn_global_load_lds((const unsigned*)((const char*)(gbase) + (voff)[_i]), (LAS unsigned*)(lds + (bufoff) + ldsw + _i * 8192), 16, 0, 0); } while (0)
; #define PG8_LDA(dst, b, h) do { _Pragma("unroll") for (int m = 0; m < 4; ++m) _Pragma("unroll") for (int k = 0; k < 2; ++k) dst[m][k] = *(const LAS bf16x8*)(lds + PG8_SA(b, h) + aoff + m * 2048 + k * 1024); } while (0)
; #define PG8_LDB(dst, b, h) do { _Pragma("unroll") for (int n = 0; n < 2; ++n) _Pragma("unroll") for (int k = 0; k < 2; ++k) dst[n][k] = *(const LAS bf16x8*)(lds + PG8_SB(b, h) + boff + n * 2048 + k * 1024); } while (0)
; #define PG8_MMA(ai, bj, At, Bt) do { __builtin_amdgcn_s_setprio(1); _Pragma("unroll") for (int m = 0; m < 4; ++m) _Pragma("unroll") for (int n = 0; n < 2; ++n) _Pragma("unroll") for (int k = 0; k < 2; ++k) \
;         acc[ai][bj][m][n] = __builtin_amdgcn_mfma_f32_16x16x32_bf16(Bt[n][k], At[m][k], acc[ai][bj][m][n], 0, 0, 0); __builtin_amdgcn_s_setprio(0); } while (0)
; #define PG8_WAIT_V(n) asm volatile("s_waitcnt vmcnt(" #n ")" ::: "memory")
; #define PG8_WAIT_L(n) asm volatile("s_waitcnt lgkmcnt(" #n ")" ::: "memory")
; #define PG8_BAR __builtin_amdgcn_s_barrier()
; #define PG8_SCHED __builtin_amdgcn_sched_barrier(0)
; template <class Epi, class Sched>
; __device__ __forceinline__ void gemm_phase(LAS unsigned char* lds, const Gemm g, const Sched& S, const Epi& E, const int wid) {
;     ...
;             PG8_WAIT_V(8); PG8_WAIT_L(0); PG8_BAR; PG8_MMA(0, 0, At, B0); PG8_MMA(0, 1, At, B1); PG8_BAR; PG8_SCHED;
;             PG8_LDA(At, 0, 1); PG8_STAGE(PG8_SB(0, 0), b2, voffB); PG8_STAGE(PG8_SB(0, 1), b2 + bstep, voffB); PG8_STAGE(PG8_SA(0, 0), a2, voffA);
;             PG8_WAIT_V(8); PG8_WAIT_L(0); PG8_BAR; PG8_MMA(1, 0, At, B0); PG8_MMA(1, 1, At, B1); PG8_BAR; PG8_SCHED;
;             PG8_LDB(B0, 1, 0); PG8_LDB(B1, 1, 1); PG8_SCHED; PG8_LDA(At, 1, 0); PG8_STAGE(PG8_SA(0, 1), a2 + hstep, voffA);
;             PG8_WAIT_V(8); PG8_WAIT_L(0); PG8_BAR; PG8_MMA(0, 0, At, B0); PG8_MMA(0, 1, At, B1); PG8_BAR; PG8_SCHED;
	s_setprio 1
	s_waitcnt lgkmcnt(0)
	v_mfma_f32_16x16x32_bf16 v[102:105], v[144:147], v[198:201], v[102:105]
	v_mfma_f32_16x16x32_bf16 v[110:113], v[162:165], v[198:201], v[110:113]
	v_mfma_f32_16x16x32_bf16 v[86:89], v[144:147], v[206:209], v[86:89]
	v_mfma_f32_16x16x32_bf16 v[94:97], v[162:165], v[206:209], v[94:97]
	v_mfma_f32_16x16x32_bf16 v[70:73], v[144:147], v[214:217], v[70:73]
	v_mfma_f32_16x16x32_bf16 v[78:81], v[162:165], v[214:217], v[78:81]
	v_mfma_f32_16x16x32_bf16 v[50:53], v[144:147], v[222:225], v[50:53]
	v_mfma_f32_16x16x32_bf16 v[62:65], v[162:165], v[222:225], v[62:65]
	v_mfma_f32_16x16x32_bf16 v[102:105], v[158:161], v[202:205], v[102:105]
	v_mfma_f32_16x16x32_bf16 v[110:113], v[166:169], v[202:205], v[110:113]
	v_mfma_f32_16x16x32_bf16 v[86:89], v[158:161], v[210:213], v[86:89]
	v_mfma_f32_16x16x32_bf16 v[94:97], v[166:169], v[210:213], v[94:97]
	v_mfma_f32_16x16x32_bf16 v[70:73], v[158:161], v[218:221], v[70:73]
	v_mfma_f32_16x16x32_bf16 v[78:81], v[166:169], v[218:221], v[78:81]
	v_mfma_f32_16x16x32_bf16 v[50:53], v[158:161], v[226:229], v[50:53]
	v_mfma_f32_16x16x32_bf16 v[62:65], v[166:169], v[226:229], v[62:65]
	s_setprio 0
	s_setprio 1
	v_mfma_f32_16x16x32_bf16 v[98:101], v[170:173], v[198:201], v[98:101]
	v_mfma_f32_16x16x32_bf16 v[106:109], v[178:181], v[198:201], v[106:109]
	v_mfma_f32_16x16x32_bf16 v[82:85], v[170:173], v[206:209], v[82:85]
	v_mfma_f32_16x16x32_bf16 v[90:93], v[178:181], v[206:209], v[90:93]
	v_mfma_f32_16x16x32_bf16 v[66:69], v[170:173], v[214:217], v[66:69]
	v_mfma_f32_16x16x32_bf16 v[74:77], v[178:181], v[214:217], v[74:77]
	v_mfma_f32_16x16x32_bf16 v[46:49], v[170:173], v[222:225], v[46:49]
	v_mfma_f32_16x16x32_bf16 v[58:61], v[178:181], v[222:225], v[58:61]
	v_mfma_f32_16x16x32_bf16 v[98:101], v[174:177], v[202:205], v[98:101]
	v_mfma_f32_16x16x32_bf16 v[106:109], v[194:197], v[202:205], v[106:109]
	v_mfma_f32_16x16x32_bf16 v[82:85], v[174:177], v[210:213], v[82:85]
	v_mfma_f32_16x16x32_bf16 v[90:93], v[194:197], v[210:213], v[90:93]
	v_mfma_f32_16x16x32_bf16 v[66:69], v[174:177], v[218:221], v[66:69]
	v_mfma_f32_16x16x32_bf16 v[74:77], v[194:197], v[218:221], v[74:77]
	v_mfma_f32_16x16x32_bf16 v[46:49], v[174:177], v[226:229], v[46:49]
	v_mfma_f32_16x16x32_bf16 v[58:61], v[194:197], v[226:229], v[58:61]
	s_setprio 0
	s_barrier
	s_add_i32 s78, 0, 0x18000
	v_add_u32_e32 v157, s78, v155
	s_add_i32 s79, 0, 0x1c000
	ds_read_b128 v[144:147], v157
	ds_read_b128 v[158:161], v157 offset:1024
	ds_read_b128 v[162:165], v157 offset:2048
	ds_read_b128 v[166:169], v157 offset:3072
	v_add_u32_e32 v157, s79, v155
	ds_read_b128 v[170:173], v157
	ds_read_b128 v[174:177], v157 offset:1024
	ds_read_b128 v[178:181], v157 offset:2048
	ds_read_b128 v[194:197], v157 offset:3072
	s_add_u32 s20, s20, 0x80000
	s_addc_u32 s21, s21, 0
	s_mov_b32 m0, s25
	v_lshl_add_u64 v[230:231], s[20:21], 0, v[134:135]
	ds_read_b128 v[198:201], v156 offset:32768
	ds_read_b128 v[202:205], v156 offset:33792
	ds_read_b128 v[206:209], v156 offset:34816
	ds_read_b128 v[210:213], v156 offset:35840
	ds_read_b128 v[214:217], v156 offset:36864
	ds_read_b128 v[218:221], v156 offset:37888
	ds_read_b128 v[222:225], v156 offset:38912
	ds_read_b128 v[226:229], v156 offset:39936
	global_load_lds_dwordx4 v[230:231], off
	v_lshl_add_u64 v[230:231], s[20:21], 0, v[132:133]
	s_mov_b32 m0, s26
	s_nop 0
	global_load_lds_dwordx4 v[230:231], off
	s_waitcnt vmcnt(8)
	s_waitcnt lgkmcnt(0)
	s_barrier
	s_setprio 1
	s_waitcnt lgkmcnt(0)
	v_mfma_f32_16x16x32_bf16 v[18:21], v[144:147], v[198:201], v[18:21]
	v_mfma_f32_16x16x32_bf16 v[38:41], v[162:165], v[198:201], v[38:41]
	v_mfma_f32_16x16x32_bf16 v[6:9], v[144:147], v[206:209], v[6:9]
	v_mfma_f32_16x16x32_bf16 v[26:29], v[162:165], v[206:209], v[26:29]
	v_mfma_f32_16x16x32_bf16 v[2:5], v[144:147], v[214:217], v[2:5]
	v_mfma_f32_16x16x32_bf16 v[14:17], v[162:165], v[214:217], v[14:17]
	v_mfma_f32_16x16x32_bf16 v[118:121], v[144:147], v[222:225], v[118:121]
	v_mfma_f32_16x16x32_bf16 v[126:129], v[162:165], v[222:225], v[126:129]
	v_mfma_f32_16x16x32_bf16 v[18:21], v[158:161], v[202:205], v[18:21]
	v_mfma_f32_16x16x32_bf16 v[38:41], v[166:169], v[202:205], v[38:41]
	v_mfma_f32_16x16x32_bf16 v[6:9], v[158:161], v[210:213], v[6:9]
	v_mfma_f32_16x16x32_bf16 v[26:29], v[166:169], v[210:213], v[26:29]
	v_mfma_f32_16x16x32_bf16 v[2:5], v[158:161], v[218:221], v[2:5]
	v_mfma_f32_16x16x32_bf16 v[14:17], v[166:169], v[218:221], v[14:17]
	v_mfma_f32_16x16x32_bf16 v[118:121], v[158:161], v[226:229], v[118:121]
	v_mfma_f32_16x16x32_bf16 v[126:129], v[166:169], v[226:229], v[126:129]
	s_setprio 0
	s_setprio 1
	v_mfma_f32_16x16x32_bf16 v[34:37], v[170:173], v[198:201], v[34:37]
	v_mfma_f32_16x16x32_bf16 v[54:57], v[178:181], v[198:201], v[54:57]
	v_mfma_f32_16x16x32_bf16 v[22:25], v[170:173], v[206:209], v[22:25]
	v_mfma_f32_16x16x32_bf16 v[42:45], v[178:181], v[206:209], v[42:45]
	v_mfma_f32_16x16x32_bf16 v[10:13], v[170:173], v[214:217], v[10:13]
	v_mfma_f32_16x16x32_bf16 v[30:33], v[178:181], v[214:217], v[30:33]
	v_mfma_f32_16x16x32_bf16 v[114:117], v[170:173], v[222:225], v[114:117]
	v_mfma_f32_16x16x32_bf16 v[122:125], v[178:181], v[222:225], v[122:125]
	v_mfma_f32_16x16x32_bf16 v[34:37], v[174:177], v[202:205], v[34:37]
	v_mfma_f32_16x16x32_bf16 v[54:57], v[194:197], v[202:205], v[54:57]
	v_mfma_f32_16x16x32_bf16 v[22:25], v[174:177], v[210:213], v[22:25]
	v_mfma_f32_16x16x32_bf16 v[42:45], v[194:197], v[210:213], v[42:45]
	v_mfma_f32_16x16x32_bf16 v[10:13], v[174:177], v[218:221], v[10:13]
	v_mfma_f32_16x16x32_bf16 v[30:33], v[194:197], v[218:221], v[30:33]
	v_mfma_f32_16x16x32_bf16 v[114:117], v[174:177], v[226:229], v[114:117]
	v_mfma_f32_16x16x32_bf16 v[122:125], v[194:197], v[226:229], v[122:125]
	s_setprio 0
	s_barrier
; #define PG8_STAGE(bufoff, gbase, voff) do { _Pragma("unroll") for (int _i = 0; _i < 2; ++_i) \
;         __builtin_amdgcn_global_load_lds((const unsigned*)((const char*)(gbase) + (voff)[_i]), (LAS unsigned*)(lds + (bufoff) + ldsw + _i * 8192), 16, 0, 0); } while (0)
; #define PG8_LDA(dst, b, h) do { _Pragma("unroll") for (int m = 0; m < 4; ++m) _Pragma("unroll") for (int k = 0; k < 2; ++k) dst[m][k] = *(const LAS bf16x8*)(lds + PG8_SA(b, h) + aoff + m * 2048 + k * 1024); } while (0)
; #define PG8_MMA(ai, bj, At, Bt) do { __builtin_amdgcn_s_setprio(1); _Pragma("unroll") for (int m = 0; m < 4; ++m) _Pragma("unroll") for (int n = 0; n < 2; ++n) _Pragma("unroll") for (int k = 0; k < 2; ++k) \
;         acc[ai][bj][m][n] = __builtin_amdgcn_mfma_f32_16x16x32_bf16(Bt[n][k], At[m][k], acc[ai][bj][m][n], 0, 0, 0); __builtin_amdgcn_s_setprio(0); } while (0)
; #define PG8_WAIT_V(n) asm volatile("s_waitcnt vmcnt(" #n ")" ::: "memory")
; #define PG8_WAIT_L(n) asm volatile("s_waitcnt lgkmcnt(" #n ")" ::: "memory")
; #define PG8_BAR __builtin_amdgcn_s_barrier()
; #define PG8_SCHED __builtin_amdgcn_sched_barrier(0)
; template <class Epi, class Sched>
; __device__ __forceinline__ void gemm_phase(LAS unsigned char* lds, const Gemm g, const Sched& S, const Epi& E, const int wid) {
;     ...
;         for (int t = 0; t < nt; t += 2) {
;     ...
;             PG8_LDA(At, 1, 1); PG8_STAGE(PG8_SB(1, 0), b3, voffB); PG8_STAGE(PG8_SB(1, 1), b3 + bstep, voffB); PG8_STAGE(PG8_SA(1, 0), a3, voffA);
;             PG8_WAIT_V(8); PG8_WAIT_L(0); PG8_BAR; PG8_MMA(1, 0, At, B0); PG8_MMA(1, 1, At, B1); PG8_BAR; PG8_SCHED;
	s_add_i32 s20, s78, s97
	v_lshl_add_u64 v[148:149], v[148:149], 0, s[86:87]
	s_mov_b32 m0, s20
	ds_read_b128 v[198:201], v156 offset:49152
	ds_read_b128 v[202:205], v156 offset:50176
	ds_read_b128 v[206:209], v156 offset:51200
	ds_read_b128 v[210:213], v156 offset:52224
	ds_read_b128 v[214:217], v156 offset:53248
	ds_read_b128 v[218:221], v156 offset:54272
	ds_read_b128 v[222:225], v156 offset:55296
	ds_read_b128 v[226:229], v156 offset:56320
	global_load_lds_dwordx4 v[148:149], off
	s_add_i32 m0, s20, 0x2000
	s_add_u32 s18, s18, 0x20080
	v_lshl_add_u64 v[148:149], v[152:153], 0, s[86:87]
	s_addc_u32 s19, s19, 0
	s_add_i32 s20, s79, s97
	global_load_lds_dwordx4 v[148:149], off
	v_lshl_add_u64 v[148:149], s[18:19], 0, v[0:1]
	s_mov_b32 m0, s20
	s_nop 0
	global_load_lds_dwordx4 v[148:149], off
	v_lshl_add_u64 v[148:149], s[18:19], 0, v[130:131]
	s_add_i32 m0, s20, 0x2000
	s_nop 0
	global_load_lds_dwordx4 v[148:149], off
	v_lshl_add_u64 v[148:149], v[182:183], 0, s[86:87]
	s_mov_b32 m0, s29
	s_nop 0
	global_load_lds_dwordx4 v[148:149], off
	v_lshl_add_u64 v[148:149], v[188:189], 0, s[86:87]
	s_mov_b32 m0, s33
	s_nop 0
	global_load_lds_dwordx4 v[148:149], off
	s_waitcnt vmcnt(8)
	s_waitcnt lgkmcnt(0)
	s_barrier
	s_setprio 1
	s_waitcnt lgkmcnt(0)
	v_mfma_f32_16x16x32_bf16 v[102:105], v[144:147], v[198:201], v[102:105]
	v_mfma_f32_16x16x32_bf16 v[110:113], v[162:165], v[198:201], v[110:113]
	v_mfma_f32_16x16x32_bf16 v[86:89], v[144:147], v[206:209], v[86:89]
	v_mfma_f32_16x16x32_bf16 v[94:97], v[162:165], v[206:209], v[94:97]
	v_mfma_f32_16x16x32_bf16 v[70:73], v[144:147], v[214:217], v[70:73]
	v_mfma_f32_16x16x32_bf16 v[78:81], v[162:165], v[214:217], v[78:81]
	v_mfma_f32_16x16x32_bf16 v[50:53], v[144:147], v[222:225], v[50:53]
	v_mfma_f32_16x16x32_bf16 v[62:65], v[162:165], v[222:225], v[62:65]
	v_mfma_f32_16x16x32_bf16 v[102:105], v[158:161], v[202:205], v[102:105]
	v_mfma_f32_16x16x32_bf16 v[110:113], v[166:169], v[202:205], v[110:113]
	v_mfma_f32_16x16x32_bf16 v[86:89], v[158:161], v[210:213], v[86:89]
	v_mfma_f32_16x16x32_bf16 v[94:97], v[166:169], v[210:213], v[94:97]
	v_mfma_f32_16x16x32_bf16 v[70:73], v[158:161], v[218:221], v[70:73]
	v_mfma_f32_16x16x32_bf16 v[78:81], v[166:169], v[218:221], v[78:81]
	v_mfma_f32_16x16x32_bf16 v[50:53], v[158:161], v[226:229], v[50:53]
	v_mfma_f32_16x16x32_bf16 v[62:65], v[166:169], v[226:229], v[62:65]
	s_setprio 0
	s_setprio 1
	v_mfma_f32_16x16x32_bf16 v[98:101], v[170:173], v[198:201], v[98:101]
	v_mfma_f32_16x16x32_bf16 v[106:109], v[178:181], v[198:201], v[106:109]
	v_mfma_f32_16x16x32_bf16 v[82:85], v[170:173], v[206:209], v[82:85]
	v_mfma_f32_16x16x32_bf16 v[90:93], v[178:181], v[206:209], v[90:93]
	v_mfma_f32_16x16x32_bf16 v[66:69], v[170:173], v[214:217], v[66:69]
	v_mfma_f32_16x16x32_bf16 v[74:77], v[178:181], v[214:217], v[74:77]
	v_mfma_f32_16x16x32_bf16 v[46:49], v[170:173], v[222:225], v[46:49]
	v_mfma_f32_16x16x32_bf16 v[58:61], v[178:181], v[222:225], v[58:61]
	v_mfma_f32_16x16x32_bf16 v[98:101], v[174:177], v[202:205], v[98:101]
	v_mfma_f32_16x16x32_bf16 v[106:109], v[194:197], v[202:205], v[106:109]
	v_mfma_f32_16x16x32_bf16 v[82:85], v[174:177], v[210:213], v[82:85]
	v_mfma_f32_16x16x32_bf16 v[90:93], v[194:197], v[210:213], v[90:93]
	v_mfma_f32_16x16x32_bf16 v[66:69], v[174:177], v[218:221], v[66:69]
	v_mfma_f32_16x16x32_bf16 v[74:77], v[194:197], v[218:221], v[74:77]
	v_mfma_f32_16x16x32_bf16 v[46:49], v[174:177], v[226:229], v[46:49]
	v_mfma_f32_16x16x32_bf16 v[58:61], v[194:197], v[226:229], v[58:61]
	s_setprio 0
	s_barrier
	s_add_i32 s51, s51, 2
	s_add_u32 s16, s16, 0x100
	s_addc_u32 s17, s17, 0
	s_cmp_gt_u32 s51, 29
	s_branch .LBB0_643
